# v33 + own-wave selection-mask LDS read hoisted above the per-tile barrier in the slc attention loops
# baseline (speedup 1.0000x reference)
; DEVI void attn_item(const Params& p, int bg, int t0, unsigned char* smem) {
;     ...
;     auto body = [&](auto kc, const int n) {
;         constexpr int KIND = decltype(kc)::value;
;         asm volatile("s_waitcnt vmcnt(0)\n\ts_barrier" ::: "memory");
;         if (n + 1 < ntot) {
;             const bf16_t *kp, *vp; tile_ptrs(n + 1, kp, vp);
;             glds_tile4(gv0, gv1, kp, vp, __builtin_amdgcn_readfirstlane(alds0 + ((n + 1) & 1) * 16384));
;         }
;         const unsigned char* cK = smem + (n & 1) * 16384;
;         const unsigned char* cV = cK + 8192;
;         constexpr bool is_p1 = KIND == 0, is_p2 = KIND == 1, is_slc = KIND == 2 || KIND == 4;
;         const int jt = is_slc ? n - n2 : jlo + (n - n3);
;         constexpr bool elem = KIND == 3 || KIND == 4;
;         const int wlim = is_slc ? 0x40000000 : 512;
;         const int c0 = (is_p1 ? n : n - n1) * 64;
;         bool any_act = true;
;         if (is_slc && !elem) {
;             const unsigned aw = __builtin_amdgcn_readfirstlane(anyw[jt >> 5] | anyw[4 + (jt >> 5)]);
;             any_act = (aw >> (jt & 31)) & 1u;
;         }
.LBB0_492:
	s_add_i32 s0, s70, s13
	s_ashr_i32 s1, s0, 5
	s_lshl_b32 s1, s1, 2
	s_add_i32 s1, s10, s1
	v_mov_b32_e32 v0, s1
	v_add_u32_e32 v0, 0xa000, v0
	ds_read2_b32 v[92:93], v0 offset0:32 offset1:36
	s_add_i32 s89, s13, 1
	s_cmp_ge_i32 s89, s22
	s_cbranch_scc1 .Lawb_c
	s_cmp_ge_u32 s89, s80
	s_mov_b64 s[68:69], -1
	s_cbranch_scc0 .LBB0_499
	s_cmp_ge_i32 s89, s81
	s_mov_b64 s[14:15], -1
	s_cbranch_scc0 .LBB0_496
	s_add_i32 s0, s91, s13
	s_mov_b64 s[14:15], 0

; DEVI void attn_item(const Params& p, int bg, int t0, unsigned char* smem) {
;     ...
;         if (is_slc && !elem) {
;             const unsigned aw = __builtin_amdgcn_readfirstlane(anyw[jt >> 5] | anyw[4 + (jt >> 5)]);
;             any_act = (aw >> (jt & 31)) & 1u;
;         }
;         if (any_act) {
;             f32x4 s[2][4];
;             {
;                 bf16x8 k0[4], k1[4];
; #pragma unroll
;                 for (int mt = 0; mt < 4; ++mt) {
;                     k0[mt] = *(const bf16x8*)(cK + (mt * 16 + l16) * 128 + ((quad ^ rsw) * 16));
;                     k1[mt] = *(const bf16x8*)(cK + (mt * 16 + l16) * 128 + (((4 + quad) ^ rsw) * 16));
;                 }
; #pragma unroll
;                 for (int mt = 0; mt < 4; ++mt)
; #pragma unroll
;                     for (int ct = 0; ct < 2; ++ct) s[ct][mt] = mfma16(k0[mt], qf[ct][0], (f32x4){0.f, 0.f, 0.f, 0.f});
; #pragma unroll
;                 for (int mt = 0; mt < 4; ++mt)
; #pragma unroll
;                     for (int ct = 0; ct < 2; ++ct) s[ct][mt] = mfma16(k1[mt], qf[ct][1], s[ct][mt]);
;     ...
;                         for (int ct = 0; ct < 2; ++ct) mr[ct] = rmax16(mr[ct]);
; #pragma unroll
;                         for (int ct = 0; ct < 2; ++ct) mr[ct] = rmax32(mr[ct]);
;                         float cand[2];
;                         bool need = false;
; #pragma unroll
;                         for (int ct = 0; ct < 2; ++ct) {
;                             cand[ct] = fmaxf(m[ct], __builtin_fmaf(mr[ct], LOG2E, bias[ct]));
;                             need = need || (cand[ct] - m[ct] > 8.0f);
;                         }
;                         const bool resc = __builtin_amdgcn_ballot_w64(need) != 0;
; #pragma unroll
;                         for (int ct = 0; ct < 2; ++ct) {
;                             mn[ct] = resc ? cand[ct] : m[ct];
;                             const float nb = bias[ct] - mn[ct];
; #pragma unroll
;                             for (int mt = 0; mt < 4; ++mt)
; #pragma unroll
;                                 for (int rr = 0; rr < 4; ++rr) { s[ct][mt][rr] = fast_exp2(__builtin_fmaf(s[ct][mt][rr], LOG2E, nb)); }
;                         }
;                     }
;                     float al[2];
; #pragma unroll
;                     for (int ct = 0; ct < 2; ++ct) {
;                         al[ct] = fast_exp2(m[ct] - mn[ct]);
;                         m[ct] = mn[ct];
.LBB0_502:
	s_add_i32 s0, s70, s13
	s_ashr_i32 s1, s0, 5
	s_lshl_b32 s0, 1, s0
	s_waitcnt lgkmcnt(0)
	v_or_b32_e32 v0, v93, v92
	s_nop 0
	v_readfirstlane_b32 s13, v0
	s_and_b32 s13, s13, s0
	s_cmp_eq_u32 s13, 0
	s_cbranch_scc1 .LBB0_490
	s_and_b32 s13, s71, 0x4000
	v_or_b32_e32 v171, s13, v160
	v_add_u32_e32 v0, v171, v161
	ds_read_b128 v[92:95], v0
	v_add_u32_e32 v2, v171, v162
	ds_read_b128 v[96:99], v2
	ds_read_b128 v[100:103], v0 offset:2048
	ds_read_b128 v[108:111], v2 offset:2048
	ds_read_b128 v[104:107], v0 offset:4096
	ds_read_b128 v[172:175], v2 offset:4096
	ds_read_b128 v[112:115], v0 offset:6144
	ds_read_b128 v[176:179], v2 offset:6144
	s_waitcnt vmcnt(5) lgkmcnt(3)
	v_mfma_f32_16x16x32_bf16 v[184:187], v[104:107], v[4:7], 0
	v_lshl_add_u32 v0, s1, 2, v170
	v_add_u32_e32 v0, 0xa000, v0
	s_waitcnt vmcnt(2)
	v_mfma_f32_16x16x32_bf16 v[188:191], v[104:107], v[12:15], 0
	v_mfma_f32_16x16x32_bf16 v[116:119], v[92:95], v[4:7], 0
	v_mfma_f32_16x16x32_bf16 v[92:95], v[92:95], v[12:15], 0
	s_waitcnt lgkmcnt(1)
	v_mfma_f32_16x16x32_bf16 v[192:195], v[112:115], v[4:7], 0
	v_mfma_f32_16x16x32_bf16 v[196:199], v[112:115], v[12:15], 0
	v_mfma_f32_16x16x32_bf16 v[120:123], v[96:99], v[8:11], v[116:119]
	s_waitcnt vmcnt(1)
	v_mfma_f32_16x16x32_bf16 v[104:107], v[96:99], v[16:19], v[92:95]
	v_mfma_f32_16x16x32_bf16 v[112:115], v[172:175], v[8:11], v[184:187]
	s_nop 4
	v_mfma_f32_16x16x32_bf16 v[96:99], v[172:175], v[16:19], v[188:191]
	ds_read2_b32 v[174:175], v0 offset1:16
	s_waitcnt lgkmcnt(0)
	v_and_b32_e32 v0, s0, v174
	v_mfma_f32_16x16x32_bf16 v[180:183], v[100:103], v[4:7], 0
	v_cmp_eq_u32_e32 vcc, 0, v0
	v_and_b32_e32 v0, s0, v175
	v_mfma_f32_16x16x32_bf16 v[100:103], v[100:103], v[12:15], 0
	v_cndmask_b32_e32 v173, 0, v147, vcc
	v_cmp_eq_u32_e32 vcc, 0, v0
	v_mfma_f32_16x16x32_bf16 v[116:119], v[108:111], v[8:11], v[180:183]
	v_max_f32_e32 v0, v120, v121
	v_max_f32_e32 v2, v122, v123
	v_mfma_f32_16x16x32_bf16 v[100:103], v[108:111], v[16:19], v[100:103]
	v_cndmask_b32_e32 v172, 0, v147, vcc
	s_nop 2
	v_mfma_f32_16x16x32_bf16 v[108:111], v[176:179], v[8:11], v[192:195]
	v_max_f32_e32 v167, v118, v119
	v_max3_f32 v167, v116, v117, v167
	v_max3_f32 v0, v0, v2, v167
	v_max_f32_e32 v2, v114, v115
	s_nop 1
	v_max_f32_e32 v167, v110, v111
	v_max3_f32 v2, v112, v113, v2
	v_max3_f32 v167, v108, v109, v167
	v_max3_f32 v0, v0, v2, v167
	v_max_f32_e32 v2, v104, v105
	v_mfma_f32_16x16x32_bf16 v[92:95], v[176:179], v[16:19], v[196:199]
	v_max_f32_e32 v167, v106, v107
	v_max_f32_e32 v168, v102, v103
	v_max3_f32 v168, v100, v101, v168
	v_max3_f32 v2, v2, v167, v168
	v_max_f32_e32 v167, v98, v99
	v_max_f32_e32 v174, v94, v94
	v_max_f32_e32 v168, v174, v95
	v_max3_f32 v167, v96, v97, v167
	v_max3_f32 v168, v92, v93, v168
	v_max3_f32 v2, v2, v167, v168
	v_mov_b32_e32 v167, v0
	s_nop 1
	v_permlane16_swap_b32_e32 v0, v167
	v_max_f32_e32 v167, v167, v167
	v_max_f32_e32 v0, v0, v0
	v_max_f32_e32 v0, v0, v167
	v_mov_b32_e32 v167, v2
	s_nop 1
	v_permlane16_swap_b32_e32 v2, v167
	v_max_f32_e32 v167, v167, v167
	v_max_f32_e32 v2, v2, v2
	v_max_f32_e32 v2, v2, v167
	v_mov_b32_e32 v167, v0
	s_nop 1
	v_permlane32_swap_b32_e32 v0, v167
	v_max_f32_e32 v167, v167, v167
	v_max_f32_e32 v0, v0, v0
	v_max_f32_e32 v0, v0, v167
	v_mov_b32_e32 v167, v2
	s_nop 1
	v_permlane32_swap_b32_e32 v2, v167
	v_max_f32_e32 v167, v167, v167
	v_max_f32_e32 v2, v2, v2
	v_max_f32_e32 v2, v2, v167
	v_fmamk_f32 v0, v0, 0x3fb8aa3b, v173
	v_fmamk_f32 v2, v2, 0x3fb8aa3b, v172
	v_max_f32_e32 v0, v166, v0
	v_max_f32_e32 v2, v165, v2
	v_sub_f32_e32 v167, v0, v166
	v_sub_f32_e32 v168, v2, v165
	v_max_f32_e32 v167, v167, v168
	v_cmp_lt_f32_e32 vcc, s16, v167
	s_cmp_eq_u64 vcc, 0
	s_cselect_b64 vcc, -1, 0
	v_cndmask_b32_e32 v167, v0, v166, vcc
	v_cndmask_b32_e32 v168, v2, v165, vcc
	v_sub_f32_e32 v0, v166, v167
	v_exp_f32_e32 v2, v0
	v_sub_f32_e32 v0, v165, v168
	v_exp_f32_e32 v0, v0
	v_cmp_neq_f32_e32 vcc, 1.0, v2
	v_cmp_neq_f32_e64 s[0:1], 1.0, v0
	s_or_b64 vcc, vcc, s[0:1]
	s_cbranch_vccz .LBB0_505
	v_pk_mul_f32 v[82:83], v[82:83], v[2:3] op_sel_hi:[1,0]
	v_pk_mul_f32 v[80:81], v[80:81], v[2:3] op_sel_hi:[1,0]
	v_pk_mul_f32 v[74:75], v[74:75], v[2:3] op_sel_hi:[1,0]
	v_pk_mul_f32 v[72:73], v[72:73], v[2:3] op_sel_hi:[1,0]
	v_pk_mul_f32 v[66:67], v[66:67], v[2:3] op_sel_hi:[1,0]
	v_pk_mul_f32 v[64:65], v[64:65], v[2:3] op_sel_hi:[1,0]
	v_pk_mul_f32 v[58:59], v[58:59], v[2:3] op_sel_hi:[1,0]
	v_pk_mul_f32 v[56:57], v[56:57], v[2:3] op_sel_hi:[1,0]
	v_pk_mul_f32 v[78:79], v[78:79], v[0:1] op_sel_hi:[1,0]
	v_pk_mul_f32 v[76:77], v[76:77], v[0:1] op_sel_hi:[1,0]
	v_pk_mul_f32 v[70:71], v[70:71], v[0:1] op_sel_hi:[1,0]
	v_pk_mul_f32 v[68:69], v[68:69], v[0:1] op_sel_hi:[1,0]
	v_pk_mul_f32 v[62:63], v[62:63], v[0:1] op_sel_hi:[1,0]
	v_pk_mul_f32 v[60:61], v[60:61], v[0:1] op_sel_hi:[1,0]
	v_pk_mul_f32 v[54:55], v[54:55], v[0:1] op_sel_hi:[1,0]
	v_pk_mul_f32 v[52:53], v[52:53], v[0:1] op_sel_hi:[1,0]
	v_pk_mul_f32 v[86:87], v[86:87], v[2:3] op_sel_hi:[1,0]
	v_pk_mul_f32 v[84:85], v[84:85], v[2:3] op_sel_hi:[1,0]
	v_pk_mul_f32 v[90:91], v[90:91], v[0:1] op_sel_hi:[1,0]
	v_pk_mul_f32 v[88:89], v[88:89], v[0:1] op_sel_hi:[1,0]

; DEVI void attn_item(const Params& p, int bg, int t0, unsigned char* smem) {
;     ...
;     auto body = [&](auto kc, const int n) {
;         constexpr int KIND = decltype(kc)::value;
;         asm volatile("s_waitcnt vmcnt(0)\n\ts_barrier" ::: "memory");
;         if (n + 1 < ntot) {
;             const bf16_t *kp, *vp; tile_ptrs(n + 1, kp, vp);
;             glds_tile4(gv0, gv1, kp, vp, __builtin_amdgcn_readfirstlane(alds0 + ((n + 1) & 1) * 16384));
;         }
;         const unsigned char* cK = smem + (n & 1) * 16384;
;         const unsigned char* cV = cK + 8192;
;         constexpr bool is_p1 = KIND == 0, is_p2 = KIND == 1, is_slc = KIND == 2 || KIND == 4;
;         const int jt = is_slc ? n - n2 : jlo + (n - n3);
;         constexpr bool elem = KIND == 3 || KIND == 4;
;         const int wlim = is_slc ? 0x40000000 : 512;
;         const int c0 = (is_p1 ? n : n - n1) * 64;
;         bool any_act = true;
;         if (is_slc && !elem) {
;             const unsigned aw = __builtin_amdgcn_readfirstlane(anyw[jt >> 5] | anyw[4 + (jt >> 5)]);
;             any_act = (aw >> (jt & 31)) & 1u;
;         }
.LBB0_641:
	s_add_i32 s0, s70, s13
	s_ashr_i32 s1, s0, 5
	s_lshl_b32 s1, s1, 2
	s_add_i32 s1, s11, s1
	v_mov_b32_e32 v0, s1
	v_add_u32_e32 v0, 0xa000, v0
	ds_read2_b32 v[92:93], v0 offset0:32 offset1:36
	s_add_i32 s88, s13, 1
	s_cmp_ge_i32 s88, s22
	s_cbranch_scc1 .Lawb_g
	s_cmp_ge_u32 s88, s80
	s_mov_b64 s[68:69], -1
	s_cbranch_scc0 .LBB0_648
	s_cmp_ge_i32 s88, s81
	s_mov_b64 s[14:15], -1
	s_cbranch_scc0 .LBB0_645
	s_add_i32 s0, s90, s13
	s_mov_b64 s[14:15], 0
